# removed the redundant first workgroup barrier of each attention unit prologue (the queue-pop barrier already orders LDS reuse)
# speedup vs baseline: 1.0082x; 1.0025x over previous
; #define LAS __attribute__((address_space(3)))
; #define WAIT_BAR0() asm volatile("s_waitcnt vmcnt(0) lgkmcnt(0)\n\ts_barrier" ::: "memory")
; #define SB_DMA(T, st) do { const unsigned base_ = lds0 + (st) * 16384 + wid * 1024; glds16(ksrc + (size_t)(T) * 64 * 512, RFL(base_)); glds16(vsrc + (size_t)(T) * 4096, RFL(base_ + 8192)); } while (0)
; DI void sb_unit(LAS char* lds, int b, int h, int qb, const bf16_t* __restrict__ Q, const bf16_t* __restrict__ K, const bf16_t* __restrict__ VT, const bf16_t* __restrict__ G, bf16_t* __restrict__ MIX) {
;     ...
;     const int tid = tid_, lane = tid & 63, r32 = lane & 31, hi = lane >> 5; const int wid = __builtin_amdgcn_readfirstlane(tid >> 6);
;     const int q0 = qb * 256, qw0 = q0 + 32 * wid, tq = qw0 + r32;
;     volatile LAS int* flags = (volatile LAS int*)(lds + MISC_OFF);
;     const unsigned lds0 = (unsigned)(uintptr_t)lds;
;     bf16x8 qf[4];
; #pragma unroll
;     for (int d0 = 0; d0 < 4; ++d0) qf[d0] = *(const bf16x8*)(Q + (size_t)(b * SEQ + tq) * 512 + h * 64 + d0 * 16 + hi * 8);
;     bf16x8 tp0, tp1, ones;
; #pragma unroll
;     for (int j = 0; j < 8; ++j) { const int kvk = 8 * (j >> 2) + 4 * hi + (j & 3); tp0[j] = (kvk > r32) ? (short)0x3F80 : (short)0; tp1[j] = (16 + kvk > r32) ? (short)0x3F80 : (short)0; ones[j] = (short)0x3F80; }
;     const int drow = 8 * wid + (lane >> 3), dch = (lane & 7) ^ ((drow >> 1) & 7);
;     const bf16_t* ksrc = K + (size_t)(b * SEQ + drow) * 512 + h * 64 + dch * 8;
;     const bf16_t* vsrc = VT + (size_t)(b * 8 + h) * (SEQ * 64) + drow * 64 + dch * 8;
;     ...
;     f32x16 o0 = splat16(0.f), o1 = splat16(0.f); float carry = 0.f; int done = 0;
;     const int nt = (q0 + 256) / 64;
;     WAIT_BAR0();
;     SB_DMA(nt - 1, 0);
;     for (int T = nt - 1, it = 0; T >= 0; --T, ++it) {
;         WAIT_BAR0();
.LBB0_363:
	s_andn2_b64 vcc, exec, s[0:1]
	s_mov_b64 s[0:1], -1
	s_cbranch_vccz .LBB0_369
	v_mov_b32_e32 v35, v236
	s_lshl_b32 s4, s15, 8
	v_readfirstlane_b32 s0, v35
	s_ashr_i32 s27, s0, 6
	s_lshl_b32 s24, s27, 5
	v_bfe_u32 v0, v35, 3, 3
	v_and_b32_e32 v100, 31, v35
	s_add_i32 s24, s24, s4
	s_lshl_b32 s0, s14, 13
	v_lshl_or_b32 v6, s27, 3, v0
	v_or_b32_e32 v101, s24, v100
	v_add_u32_e32 v4, s0, v6
	v_add_u32_e32 v92, s0, v101
	v_ashrrev_i32_e32 v5, 31, v4
	v_readlane_b32 s0, v253, 4
	v_lshlrev_b64 v[4:5], 10, v[4:5]
	v_readlane_b32 s1, v253, 5
	v_lshrrev_b32_e32 v0, 1, v6
	s_lshl_b32 s98, s16, 7
	v_lshl_add_u64 v[4:5], s[0:1], 0, v[4:5]
	s_lshl_b32 s0, s14, 3
	v_xor_b32_e32 v0, v0, v35
	v_lshl_add_u64 v[4:5], v[4:5], 0, s[98:99]
	s_add_i32 s98, s0, s16
	s_lshl_b32 s23, s16, 6
	v_lshlrev_b32_e32 v0, 4, v0
	s_lshl_b64 s[0:1], s[98:99], 20
	v_readlane_b32 s6, v253, 14
	v_and_b32_e32 v0, 0x70, v0
	v_readlane_b32 s7, v253, 15
	s_add_u32 s0, s6, s0
	v_lshl_add_u64 v[96:97], v[4:5], 0, v[0:1]
	s_addc_u32 s1, s7, s1
	v_lshlrev_b32_e32 v4, 6, v6
	s_addk_i32 s4, 0x100
	v_ashrrev_i32_e32 v5, 31, v4
	s_ashr_i32 s38, s4, 6
	v_lshl_add_u64 v[4:5], v[4:5], 1, s[0:1]
	s_add_i32 s0, s38, -1
	s_ashr_i32 s1, s0, 31
	s_waitcnt lgkmcnt(0)
	s_nop 0
	s_lshl_b32 s25, s27, 10
	s_lshl_b64 s[4:5], s[0:1], 16
	v_lshl_add_u64 v[98:99], v[4:5], 0, v[0:1]
	v_lshl_add_u64 v[4:5], v[96:97], 0, s[4:5]
	s_add_i32 s25, s25, 0
	s_and_b32 s46, s0, 7
	s_lshl_b32 s46, s46, 14
	s_add_i32 s46, s46, s25
	s_mov_b32 s4, m0
	s_mov_b32 m0, s46
	s_nop 0
	global_load_lds_dwordx4 v[4:5], off
	s_mov_b32 m0, s4
	s_lshl_b64 s[4:5], s[0:1], 13
	v_bfe_u32 v2, v35, 5, 1
	v_lshl_add_u64 v[4:5], v[98:99], 0, s[4:5]
	s_add_i32 s1, s46, 0x2000
	s_mov_b32 s4, m0
	s_mov_b32 m0, s1
	s_nop 0
	global_load_lds_dwordx4 v[4:5], off
	s_mov_b32 m0, s4
	s_add_i32 s47, s0, -1
	s_and_b32 s48, s47, 7
	s_lshl_b32 s48, s48, 14
	s_add_i32 s48, s48, s25
	s_mov_b32 s50, s47
	s_mov_b32 s51, 0
	s_lshl_b64 s[50:51], s[50:51], 16
	v_lshl_add_u64 v[4:5], v[96:97], 0, s[50:51]
	s_mov_b32 m0, s48
	s_nop 0
	global_load_lds_dwordx4 v[4:5], off
	s_mov_b32 s50, s47
	s_mov_b32 s51, 0
	s_lshl_b64 s[50:51], s[50:51], 13
	v_lshl_add_u64 v[4:5], v[98:99], 0, s[50:51]
	s_add_i32 s48, s48, 0x2000
	s_mov_b32 m0, s48
	s_nop 0
	global_load_lds_dwordx4 v[4:5], off
	s_add_i32 s47, s0, -2
	s_and_b32 s48, s47, 7
	s_lshl_b32 s48, s48, 14
	s_add_i32 s48, s48, s25
	s_mov_b32 s50, s47
	s_mov_b32 s51, 0
	s_lshl_b64 s[50:51], s[50:51], 16
	v_lshl_add_u64 v[4:5], v[96:97], 0, s[50:51]
	s_mov_b32 m0, s48
	s_nop 0
	global_load_lds_dwordx4 v[4:5], off
	s_mov_b32 s50, s47
	s_mov_b32 s51, 0
	s_lshl_b64 s[50:51], s[50:51], 13
	v_lshl_add_u64 v[4:5], v[98:99], 0, s[50:51]
	s_add_i32 s48, s48, 0x2000
	s_mov_b32 m0, s48
	s_nop 0
	global_load_lds_dwordx4 v[4:5], off
	s_add_i32 s47, s0, -3
	s_and_b32 s48, s47, 7
	s_lshl_b32 s48, s48, 14
	s_add_i32 s48, s48, s25
	s_mov_b32 s50, s47
	s_mov_b32 s51, 0
	s_lshl_b64 s[50:51], s[50:51], 16
	v_lshl_add_u64 v[4:5], v[96:97], 0, s[50:51]
	s_mov_b32 m0, s48
	s_nop 0
	global_load_lds_dwordx4 v[4:5], off
	s_mov_b32 s50, s47
	s_mov_b32 s51, 0
	s_lshl_b64 s[50:51], s[50:51], 13
	v_lshl_add_u64 v[4:5], v[98:99], 0, s[50:51]
	s_add_i32 s48, s48, 0x2000
	s_mov_b32 m0, s48
	s_nop 0
	global_load_lds_dwordx4 v[4:5], off
	v_ashrrev_i32_e32 v93, 31, v92
	v_lshlrev_b32_e32 v3, 3, v2
	v_lshlrev_b64 v[94:95], 10, v[92:93]
	s_cmp_lt_i32 s38, 1
	v_lshlrev_b32_e32 v0, 1, v3
	s_cbranch_scc1 .LBB0_371
	v_readlane_b32 s4, v253, 2
	v_readlane_b32 s5, v253, 3
	s_lshl_b32 s98, s23, 1
	v_lshlrev_b32_e32 v102, 2, v2
	v_lshl_add_u64 v[4:5], s[4:5], 0, v[94:95]
	v_lshl_add_u64 v[4:5], v[4:5], 0, s[98:99]
	v_lshl_add_u64 v[4:5], v[4:5], 0, v[0:1]
	global_load_dwordx4 v[68:71], v[4:5], off
	global_load_dwordx4 v[72:75], v[4:5], off offset:32
	global_load_dwordx4 v[76:79], v[4:5], off offset:64
	global_load_dwordx4 v[80:83], v[4:5], off offset:96
	v_or_b32_e32 v3, 16, v102
	v_cmp_gt_u32_e32 vcc, v3, v100
	v_mov_b32_e32 v15, 0x3f80
	v_or_b32_e32 v5, 17, v102
	v_cndmask_b32_e32 v3, 0, v15, vcc
	v_or_b32_e32 v4, 18, v102
	v_cmp_gt_u32_e32 vcc, v5, v100
	v_or_b32_e32 v7, 19, v102
	v_or_b32_e32 v6, 24, v102
	v_cndmask_b32_e32 v5, 0, v15, vcc
	v_cmp_gt_u32_e32 vcc, v4, v100
	v_or_b32_e32 v8, 26, v102
	v_or_b32_e32 v9, 25, v102
	v_cndmask_b32_e32 v4, 0, v15, vcc
	v_cmp_gt_u32_e32 vcc, v7, v100
	v_or_b32_e32 v10, 27, v102
	s_mov_b32 s1, 0x5040100
	v_cndmask_b32_e32 v7, 0, v15, vcc
	v_cmp_gt_u32_e32 vcc, v6, v100
	v_or_b32_e32 v12, 10, v102
	v_or_b32_e32 v11, 11, v102
	v_cndmask_b32_e32 v6, 0, v15, vcc
	v_cmp_gt_u32_e32 vcc, v8, v100
	v_perm_b32 v88, v5, v3, s1
	s_add_i32 s98, s38, -2
	v_cndmask_b32_e32 v8, 0, v15, vcc
	v_cmp_gt_u32_e32 vcc, v9, v100
	s_waitcnt vmcnt(0) lgkmcnt(0)
	s_barrier
; #define LAS __attribute__((address_space(3)))
; #define MFMA32(a, b, c) __builtin_amdgcn_mfma_f32_32x32x16_bf16((a), (b), (c), 0, 0, 0)
; DI int crow(int r, int hi) { return (r & 3) + 8 * (r >> 2) + 4 * hi; }
; DI float ex2(float x) { return __builtin_amdgcn_exp2f(x); }
; DI float lg2(float x) { return __builtin_amdgcn_logf(x); }
; DI void sb_unit(LAS char* lds, int b, int h, int qb, const bf16_t* __restrict__ Q, const bf16_t* __restrict__ K, const bf16_t* __restrict__ VT, const bf16_t* __restrict__ G, bf16_t* __restrict__ MIX) {
;     ...
;     for (int j = 0; j < 8; ++j) { const int kvk = 8 * (j >> 2) + 4 * hi + (j & 3); tp0[j] = (kvk > r32) ? (short)0x3F80 : (short)0; tp1[j] = (16 + kvk > r32) ? (short)0x3F80 : (short)0; ones[j] = (short)0x3F80; }
;     const int drow = 8 * wid + (lane >> 3), dch = (lane & 7) ^ ((drow >> 1) & 7);
;     const bf16_t* ksrc = K + (size_t)(b * SEQ + drow) * 512 + h * 64 + dch * 8;
;     const bf16_t* vsrc = VT + (size_t)(b * 8 + h) * (SEQ * 64) + drow * 64 + dch * 8;
;     ...
;         const LAS char* Kt = lds + (it & 1) * 16384; const LAS char* Vt = Kt + 8192;
;         const int kv0 = 64 * T;
;         if (kv0 < qw0 + 31 && !done) {
;             f32x16 p0 = splat16(0.f), p1 = splat16(0.f);
; #pragma unroll
;             for (int d0 = 0; d0 < 4; ++d0) { const bf16x8 k0 = ldsv(Kt + off128(r32, 2 * d0 + hi)), k1 = ldsv(Kt + off128(32 + r32, 2 * d0 + hi)); p0 = MFMA32(k0, qf[d0], p0); p1 = MFMA32(k1, qf[d0], p1); }
;             const bool diag = (kv0 + 63 >= qw0);
;             f32x16 L0, L1;
; #pragma unroll
;             for (int r = 0; r < 16; ++r) {
;                 { const float z = p0[r]; const float lg = (z > 30.f) ? z : lg2(1.0f + ex2(z)); const bool valid = !diag || (kv0 + crow(r, hi) < tq); L0[r] = valid ? -lg : 0.f; p0[r] = valid ? (z - lg) : -1e30f; }
;                 { const float z = p1[r]; const float lg = (z > 30.f) ? z : lg2(1.0f + ex2(z)); const bool valid = !diag || (kv0 + 32 + crow(r, hi) < tq); L1[r] = valid ? -lg : 0.f; p1[r] = valid ? (z - lg) : -1e30f; }
;             }
	s_lshl_b64 s[4:5], s[98:99], 16
	v_perm_b32 v89, v7, v4, s1
	v_cndmask_b32_e32 v9, 0, v15, vcc
	v_cmp_gt_u32_e32 vcc, v10, v100
	v_perm_b32 v90, v9, v6, s1
	s_or_b32 s26, s24, 31
	v_cndmask_b32_e32 v10, 0, v15, vcc
	v_cmp_gt_u32_e32 vcc, v102, v100
	v_perm_b32 v91, v10, v8, s1
	v_lshlrev_b32_e32 v103, 7, v100
	v_cndmask_b32_e32 v13, 0, v15, vcc
	v_cmp_lt_u32_e32 vcc, v102, v100
	s_nop 1
	v_cndmask_b32_e64 v14, v15, 0, vcc
	v_perm_b32 v84, v14, v13, s1
	v_or_b32_e32 v14, 2, v102
	v_or_b32_e32 v13, 3, v102
	v_cmp_gt_u32_e32 vcc, v14, v100
	s_nop 1
	v_cndmask_b32_e32 v14, 0, v15, vcc
	v_cmp_gt_u32_e32 vcc, v13, v100
	s_nop 1
	v_cndmask_b32_e32 v13, 0, v15, vcc
	v_perm_b32 v85, v13, v14, s1
	v_or_b32_e32 v14, 8, v102
	v_or_b32_e32 v13, 9, v102
	v_cmp_gt_u32_e32 vcc, v14, v100
	s_nop 1
	v_cndmask_b32_e32 v14, 0, v15, vcc
	v_cmp_gt_u32_e32 vcc, v13, v100
	s_nop 1
	v_cndmask_b32_e32 v13, 0, v15, vcc
	v_cmp_gt_u32_e32 vcc, v12, v100
	v_perm_b32 v86, v13, v14, s1
	s_nop 0
	v_cndmask_b32_e32 v12, 0, v15, vcc
	v_cmp_gt_u32_e32 vcc, v11, v100
	s_nop 1
	v_cndmask_b32_e32 v11, 0, v15, vcc
	v_perm_b32 v87, v11, v12, s1
	v_lshrrev_b32_e32 v11, 1, v35
	v_bfe_u32 v12, v35, 1, 3
	v_bitop3_b32 v3, v11, v2, 7 bitop3:0x6c
	v_lshlrev_b32_e32 v104, 4, v3
	v_bitop3_b32 v3, v2, v12, 2 bitop3:0x36
	v_lshlrev_b32_e32 v105, 4, v3
	v_bitop3_b32 v3, v2, v12, 4 bitop3:0x36
	v_bitop3_b32 v2, v2, v12, 6 bitop3:0x36
	v_lshlrev_b32_e32 v106, 4, v3
	v_lshlrev_b32_e32 v107, 4, v2
	v_lshl_add_u64 v[2:3], v[96:97], 0, s[4:5]
	s_add_i32 s1, s25, 0x4000
	s_mov_b32 s4, m0
	s_mov_b32 m0, s1
	s_nop 0
	s_nop 0
	s_mov_b32 m0, s4
	s_lshl_b64 s[4:5], s[98:99], 13
	v_lshl_add_u64 v[2:3], v[98:99], 0, s[4:5]
	s_add_i32 s1, s25, 0x6000
	s_lshl_b32 s4, s0, 6
	s_mov_b32 s0, m0
	s_mov_b32 m0, s1
	s_nop 0
	s_nop 0
	s_mov_b32 m0, s0
	s_nop 0
	s_branch .LBB0_413
	v_add_u32_e32 v34, 0, v103
	v_add_u32_e32 v6, v34, v104
	ds_read_b128 v[2:5], v6
	ds_read_b128 v[6:9], v6 offset:4096
	v_add_u32_e32 v40, v34, v105
	ds_read_b128 v[36:39], v40
	ds_read_b128 v[40:43], v40 offset:4096
	s_or_b32 s0, s4, 63
	s_waitcnt lgkmcnt(3)
	v_mfma_f32_32x32x16_bf16 v[18:33], v[2:5], v[68:71], 0
	s_cmp_lt_i32 s0, s24
	s_cselect_b64 s[0:1], -1, 0
	s_waitcnt lgkmcnt(2)
	v_mfma_f32_32x32x16_bf16 v[2:17], v[6:9], v[68:71], 0
	s_waitcnt lgkmcnt(1)
	v_mfma_f32_32x32x16_bf16 v[18:33], v[36:39], v[72:75], v[18:33]
	s_waitcnt lgkmcnt(0)
	v_mfma_f32_32x32x16_bf16 v[2:17], v[40:43], v[72:75], v[2:17]
	v_add_u32_e32 v40, v34, v106
	ds_read_b128 v[36:39], v40
	ds_read_b128 v[40:43], v40 offset:4096
	v_add_u32_e32 v34, v34, v107
	s_waitcnt lgkmcnt(1)
	v_mfma_f32_32x32x16_bf16 v[18:33], v[36:39], v[76:79], v[18:33]
	s_waitcnt lgkmcnt(0)
	v_mfma_f32_32x32x16_bf16 v[2:17], v[40:43], v[76:79], v[2:17]
	ds_read_b128 v[36:39], v34
	ds_read_b128 v[40:43], v34 offset:4096
	s_waitcnt lgkmcnt(1)
	v_mfma_f32_32x32x16_bf16 v[18:33], v[36:39], v[80:83], v[18:33]
	s_waitcnt lgkmcnt(0)
	v_mfma_f32_32x32x16_bf16 v[2:17], v[40:43], v[80:83], v[2:17]
	s_nop 9
	v_exp_f32_e32 v34, v18
	v_or_b32_e32 v41, s4, v102
	v_cmp_lt_f32_e32 vcc, s22, v18
	v_or_b32_e32 v37, 32, v41
	v_add_f32_e32 v34, 1.0, v34
	v_log_f32_e32 v34, v34
	v_or_b32_e32 v61, 24, v41
	v_readlane_b32 s4, v254, 48
	v_readlane_b32 s6, v254, 50
	v_cndmask_b32_e32 v36, v34, v18, vcc
	v_cmp_lt_i32_e32 vcc, v41, v101
	s_or_b64 vcc, s[0:1], vcc
	v_sub_f32_e32 v18, v18, v36
	v_cndmask_b32_e64 v34, 0, -v36, vcc
	v_cndmask_b32_e32 v36, v237, v18, vcc
	v_exp_f32_e32 v18, v2
	v_cmp_lt_f32_e32 vcc, s22, v2
	v_readlane_b32 s7, v254, 51
	v_readlane_b32 s5, v254, 49
	v_add_f32_e32 v18, 1.0, v18
	v_log_f32_e32 v18, v18
	s_mov_b32 s6, s4
	s_mov_b32 s7, s4
	s_mov_b32 s5, s4
	v_cndmask_b32_e32 v38, v18, v2, vcc
	v_cmp_lt_i32_e32 vcc, v37, v101
	s_or_b64 vcc, s[0:1], vcc
	v_sub_f32_e32 v2, v2, v38
	v_cndmask_b32_e32 v37, v237, v2, vcc
	v_exp_f32_e32 v2, v19
	v_cndmask_b32_e64 v18, 0, -v38, vcc
	v_cmp_lt_f32_e32 vcc, s22, v19
	v_add_f32_e32 v2, 1.0, v2
	v_log_f32_e32 v2, v2
	s_nop 0
	v_cndmask_b32_e32 v38, v2, v19, vcc
	v_or_b32_e32 v2, 1, v41
	v_cmp_lt_i32_e32 vcc, v2, v101
	s_or_b64 vcc, s[0:1], vcc
	v_sub_f32_e32 v19, v19, v38
	v_cndmask_b32_e64 v2, 0, -v38, vcc
	v_cndmask_b32_e32 v38, v237, v19, vcc
	v_exp_f32_e32 v19, v3
	v_cmp_lt_f32_e32 vcc, s22, v3
	v_cvt_pk_bf16_f32 v2, v34, v2
	v_add_f32_e32 v19, 1.0, v19
	v_log_f32_e32 v19, v19
	s_nop 0
	v_cndmask_b32_e32 v39, v19, v3, vcc
	v_or_b32_e32 v19, 33, v41
	v_cmp_lt_i32_e32 vcc, v19, v101
	s_or_b64 vcc, s[0:1], vcc
	v_sub_f32_e32 v3, v3, v39
	v_cndmask_b32_e64 v19, 0, -v39, vcc
	v_cndmask_b32_e32 v39, v237, v3, vcc
	v_exp_f32_e32 v3, v20
	v_cmp_lt_f32_e32 vcc, s22, v20
	v_cvt_pk_bf16_f32 v18, v18, v19
	v_add_f32_e32 v3, 1.0, v3
	v_log_f32_e32 v3, v3
	s_nop 0
	v_cndmask_b32_e32 v40, v3, v20, vcc
	v_or_b32_e32 v3, 2, v41
	v_cmp_lt_i32_e32 vcc, v3, v101
	s_or_b64 vcc, s[0:1], vcc
	v_sub_f32_e32 v20, v20, v40
	v_cndmask_b32_e64 v3, 0, -v40, vcc
	v_cndmask_b32_e32 v40, v237, v20, vcc
	v_exp_f32_e32 v20, v4
	v_cmp_lt_f32_e32 vcc, s22, v4
	v_add_f32_e32 v20, 1.0, v20
	v_log_f32_e32 v20, v20
	s_nop 0
	v_cndmask_b32_e32 v42, v20, v4, vcc
	v_or_b32_e32 v20, 34, v41
	v_cmp_lt_i32_e32 vcc, v20, v101
	s_or_b64 vcc, s[0:1], vcc
	v_sub_f32_e32 v4, v4, v42
	v_cndmask_b32_e64 v20, 0, -v42, vcc
	v_cndmask_b32_e32 v42, v237, v4, vcc
	v_exp_f32_e32 v4, v21
	v_cmp_lt_f32_e32 vcc, s22, v21
	v_add_f32_e32 v4, 1.0, v4
	v_log_f32_e32 v4, v4
	s_nop 0
	v_cndmask_b32_e32 v43, v4, v21, vcc
	v_or_b32_e32 v4, 3, v41
	v_cmp_lt_i32_e32 vcc, v4, v101
	s_or_b64 vcc, s[0:1], vcc
	v_sub_f32_e32 v21, v21, v43
	v_cndmask_b32_e64 v4, 0, -v43, vcc
	v_cndmask_b32_e32 v43, v237, v21, vcc
; DI int crow(int r, int hi) { return (r & 3) + 8 * (r >> 2) + 4 * hi; }
; DI float ex2(float x) { return __builtin_amdgcn_exp2f(x); }
; DI float lg2(float x) { return __builtin_amdgcn_logf(x); }
; template <int S> DI bf16x8 pack8(const f32x16& x) { u32x4 p; p[0] = cvtpk(x[8 * S], x[8 * S + 1]); p[1] = cvtpk(x[8 * S + 2], x[8 * S + 3]); p[2] = cvtpk(x[8 * S + 4], x[8 * S + 5]); p[3] = cvtpk(x[8 * S + 6], x[8 * S + 7]); return __builtin_bit_cast(bf16x8, p); }
; DI void sb_unit(LAS char* lds, int b, int h, int qb, const bf16_t* __restrict__ Q, const bf16_t* __restrict__ K, const bf16_t* __restrict__ VT, const bf16_t* __restrict__ G, bf16_t* __restrict__ MIX) {
;     ...
;             for (int r = 0; r < 16; ++r) {
;                 { const float z = p0[r]; const float lg = (z > 30.f) ? z : lg2(1.0f + ex2(z)); const bool valid = !diag || (kv0 + crow(r, hi) < tq); L0[r] = valid ? -lg : 0.f; p0[r] = valid ? (z - lg) : -1e30f; }
;                 { const float z = p1[r]; const float lg = (z > 30.f) ? z : lg2(1.0f + ex2(z)); const bool valid = !diag || (kv0 + 32 + crow(r, hi) < tq); L1[r] = valid ? -lg : 0.f; p1[r] = valid ? (z - lg) : -1e30f; }
;             }
;             const bf16x8 Lh0 = pack8<0>(L0), Lh1 = pack8<1>(L0), Lh2 = pack8<0>(L1), Lh3 = pack8<1>(L1);
	v_exp_f32_e32 v21, v5
	v_cmp_lt_f32_e32 vcc, s22, v5
	v_cvt_pk_bf16_f32 v3, v3, v4
	v_add_f32_e32 v21, 1.0, v21
	v_log_f32_e32 v21, v21
	s_nop 0
	v_cndmask_b32_e32 v44, v21, v5, vcc
	v_or_b32_e32 v21, 35, v41
	v_cmp_lt_i32_e32 vcc, v21, v101
	s_or_b64 vcc, s[0:1], vcc
	v_sub_f32_e32 v5, v5, v44
	v_cndmask_b32_e64 v21, 0, -v44, vcc
	v_cndmask_b32_e32 v44, v237, v5, vcc
	v_exp_f32_e32 v5, v22
	v_cmp_lt_f32_e32 vcc, s22, v22
	v_cvt_pk_bf16_f32 v19, v20, v21
	v_add_f32_e32 v5, 1.0, v5
	v_log_f32_e32 v5, v5
	s_nop 0
	v_cndmask_b32_e32 v45, v5, v22, vcc
	v_or_b32_e32 v5, 8, v41
	v_cmp_lt_i32_e32 vcc, v5, v101
	s_or_b64 vcc, s[0:1], vcc
	v_sub_f32_e32 v22, v22, v45
	v_cndmask_b32_e64 v5, 0, -v45, vcc
	v_cndmask_b32_e32 v45, v237, v22, vcc
	v_exp_f32_e32 v22, v6
	v_cmp_lt_f32_e32 vcc, s22, v6
	v_add_f32_e32 v22, 1.0, v22
	v_log_f32_e32 v22, v22
	s_nop 0
	v_cndmask_b32_e32 v46, v22, v6, vcc
	v_or_b32_e32 v22, 40, v41
	v_cmp_lt_i32_e32 vcc, v22, v101
	s_or_b64 vcc, s[0:1], vcc
	v_sub_f32_e32 v6, v6, v46
	v_cndmask_b32_e64 v22, 0, -v46, vcc
	v_cndmask_b32_e32 v46, v237, v6, vcc
	v_exp_f32_e32 v6, v23
	v_cmp_lt_f32_e32 vcc, s22, v23
	v_add_f32_e32 v6, 1.0, v6
	v_log_f32_e32 v6, v6
	s_nop 0
	v_cndmask_b32_e32 v47, v6, v23, vcc
	v_or_b32_e32 v6, 9, v41
	v_cmp_lt_i32_e32 vcc, v6, v101
	s_or_b64 vcc, s[0:1], vcc
	v_sub_f32_e32 v23, v23, v47
	v_cndmask_b32_e64 v6, 0, -v47, vcc
	v_cndmask_b32_e32 v47, v237, v23, vcc
	v_exp_f32_e32 v23, v7
	v_cmp_lt_f32_e32 vcc, s22, v7
	v_cvt_pk_bf16_f32 v4, v5, v6
	v_add_f32_e32 v23, 1.0, v23
	v_log_f32_e32 v23, v23
	s_nop 0
	v_cndmask_b32_e32 v48, v23, v7, vcc
	v_or_b32_e32 v23, 41, v41
	v_cmp_lt_i32_e32 vcc, v23, v101
	s_or_b64 vcc, s[0:1], vcc
	v_sub_f32_e32 v7, v7, v48
	v_cndmask_b32_e64 v23, 0, -v48, vcc
	v_cndmask_b32_e32 v48, v237, v7, vcc
	v_exp_f32_e32 v7, v24
	v_cmp_lt_f32_e32 vcc, s22, v24
	v_cvt_pk_bf16_f32 v20, v22, v23
	v_add_f32_e32 v7, 1.0, v7
	v_log_f32_e32 v7, v7
	s_nop 0
	v_cndmask_b32_e32 v49, v7, v24, vcc
	v_or_b32_e32 v7, 10, v41
	v_cmp_lt_i32_e32 vcc, v7, v101
	s_or_b64 vcc, s[0:1], vcc
	v_sub_f32_e32 v24, v24, v49
	v_cndmask_b32_e64 v7, 0, -v49, vcc
	v_cndmask_b32_e32 v49, v237, v24, vcc
	v_exp_f32_e32 v24, v8
	v_cmp_lt_f32_e32 vcc, s22, v8
	v_add_f32_e32 v24, 1.0, v24
	v_log_f32_e32 v24, v24
	s_nop 0
	v_cndmask_b32_e32 v50, v24, v8, vcc
	v_or_b32_e32 v24, 42, v41
	v_cmp_lt_i32_e32 vcc, v24, v101
	s_or_b64 vcc, s[0:1], vcc
	v_sub_f32_e32 v8, v8, v50
	v_cndmask_b32_e64 v24, 0, -v50, vcc
	v_cndmask_b32_e32 v50, v237, v8, vcc
	v_exp_f32_e32 v8, v25
	v_cmp_lt_f32_e32 vcc, s22, v25
	v_add_f32_e32 v8, 1.0, v8
	v_log_f32_e32 v8, v8
	s_nop 0
	v_cndmask_b32_e32 v51, v8, v25, vcc
	v_or_b32_e32 v8, 11, v41
	v_cmp_lt_i32_e32 vcc, v8, v101
	s_or_b64 vcc, s[0:1], vcc
	v_sub_f32_e32 v25, v25, v51
	v_cndmask_b32_e64 v8, 0, -v51, vcc
	v_cndmask_b32_e32 v51, v237, v25, vcc
	v_exp_f32_e32 v25, v9
	v_cmp_lt_f32_e32 vcc, s22, v9
	v_cvt_pk_bf16_f32 v5, v7, v8
	v_add_f32_e32 v25, 1.0, v25
	v_log_f32_e32 v25, v25
	s_nop 0
	v_cndmask_b32_e32 v52, v25, v9, vcc
	v_or_b32_e32 v25, 43, v41
	v_cmp_lt_i32_e32 vcc, v25, v101
	s_or_b64 vcc, s[0:1], vcc
	v_sub_f32_e32 v9, v9, v52
	v_cndmask_b32_e64 v25, 0, -v52, vcc
	v_cndmask_b32_e32 v52, v237, v9, vcc
	v_exp_f32_e32 v9, v26
	v_cmp_lt_f32_e32 vcc, s22, v26
	v_cvt_pk_bf16_f32 v21, v24, v25
	v_mov_b64_e32 v[24:25], s[6:7]
	v_add_f32_e32 v9, 1.0, v9
	v_log_f32_e32 v9, v9
	v_mov_b64_e32 v[22:23], s[4:5]
	v_cndmask_b32_e32 v53, v9, v26, vcc
	v_or_b32_e32 v9, 16, v41
	v_cmp_lt_i32_e32 vcc, v9, v101
	s_or_b64 vcc, s[0:1], vcc
	v_sub_f32_e32 v26, v26, v53
	v_cndmask_b32_e64 v9, 0, -v53, vcc
	v_cndmask_b32_e32 v53, v237, v26, vcc
	v_exp_f32_e32 v26, v10
	v_cmp_lt_f32_e32 vcc, s22, v10
	v_add_f32_e32 v26, 1.0, v26
	v_log_f32_e32 v26, v26
	s_nop 0
	v_cndmask_b32_e32 v54, v26, v10, vcc
	v_or_b32_e32 v26, 48, v41
	v_cmp_lt_i32_e32 vcc, v26, v101
	s_or_b64 vcc, s[0:1], vcc
	v_sub_f32_e32 v10, v10, v54
	v_cndmask_b32_e64 v26, 0, -v54, vcc
	v_cndmask_b32_e32 v54, v237, v10, vcc
	v_exp_f32_e32 v10, v27
	v_cmp_lt_f32_e32 vcc, s22, v27
	v_add_f32_e32 v10, 1.0, v10
	v_log_f32_e32 v10, v10
	s_nop 0
	v_cndmask_b32_e32 v55, v10, v27, vcc
	v_or_b32_e32 v10, 17, v41
	v_cmp_lt_i32_e32 vcc, v10, v101
	s_or_b64 vcc, s[0:1], vcc
	v_sub_f32_e32 v27, v27, v55
	v_cndmask_b32_e64 v10, 0, -v55, vcc
	v_cndmask_b32_e32 v55, v237, v27, vcc
	v_exp_f32_e32 v27, v11
	v_cmp_lt_f32_e32 vcc, s22, v11
	v_add_f32_e32 v27, 1.0, v27
	v_log_f32_e32 v27, v27
	s_nop 0
	v_cndmask_b32_e32 v56, v27, v11, vcc
	v_or_b32_e32 v27, 49, v41
	v_cmp_lt_i32_e32 vcc, v27, v101
	s_or_b64 vcc, s[0:1], vcc
	v_sub_f32_e32 v11, v11, v56
	v_cndmask_b32_e64 v27, 0, -v56, vcc
	v_cndmask_b32_e32 v56, v237, v11, vcc
	v_exp_f32_e32 v11, v28
	v_cmp_lt_f32_e32 vcc, s22, v28
	v_cvt_pk_bf16_f32 v108, v26, v27
	v_add_f32_e32 v11, 1.0, v11
	v_log_f32_e32 v11, v11
	s_nop 0
	v_cndmask_b32_e32 v57, v11, v28, vcc
	v_or_b32_e32 v11, 18, v41
	v_cmp_lt_i32_e32 vcc, v11, v101
	s_or_b64 vcc, s[0:1], vcc
	v_sub_f32_e32 v28, v28, v57
	v_cndmask_b32_e64 v11, 0, -v57, vcc
	v_cndmask_b32_e32 v57, v237, v28, vcc
	v_exp_f32_e32 v28, v12
	v_cmp_lt_f32_e32 vcc, s22, v12
	v_add_f32_e32 v28, 1.0, v28
	v_log_f32_e32 v28, v28
	s_nop 0
	v_cndmask_b32_e32 v58, v28, v12, vcc
	v_or_b32_e32 v28, 50, v41
	v_cmp_lt_i32_e32 vcc, v28, v101
	s_or_b64 vcc, s[0:1], vcc
	v_sub_f32_e32 v12, v12, v58
	v_cndmask_b32_e64 v28, 0, -v58, vcc
	v_cndmask_b32_e32 v58, v237, v12, vcc
	v_exp_f32_e32 v12, v29
	v_cmp_lt_f32_e32 vcc, s22, v29
	v_add_f32_e32 v12, 1.0, v12
	v_log_f32_e32 v12, v12
	s_nop 0
	v_cndmask_b32_e32 v59, v12, v29, vcc
	v_or_b32_e32 v12, 19, v41
	v_cmp_lt_i32_e32 vcc, v12, v101
; #define MFMA32(a, b, c) __builtin_amdgcn_mfma_f32_32x32x16_bf16((a), (b), (c), 0, 0, 0)
; DI int crow(int r, int hi) { return (r & 3) + 8 * (r >> 2) + 4 * hi; }
; DI float ex2(float x) { return __builtin_amdgcn_exp2f(x); }
; DI float lg2(float x) { return __builtin_amdgcn_logf(x); }
; template <int S> DI bf16x8 pack8(const f32x16& x) { u32x4 p; p[0] = cvtpk(x[8 * S], x[8 * S + 1]); p[1] = cvtpk(x[8 * S + 2], x[8 * S + 3]); p[2] = cvtpk(x[8 * S + 4], x[8 * S + 5]); p[3] = cvtpk(x[8 * S + 6], x[8 * S + 7]); return __builtin_bit_cast(bf16x8, p); }
; #define SB_PV(ks, pa) { const bf16x8 v0 = ldsv(Vt + off128(r32, 2 * (ks) + hi)), v1 = ldsv(Vt + off128(32 + r32, 2 * (ks) + hi)); o0 = MFMA32(v0, pa, o0); o1 = MFMA32(v1, pa, o1); }
; DI void sb_unit(LAS char* lds, int b, int h, int qb, const bf16_t* __restrict__ Q, const bf16_t* __restrict__ K, const bf16_t* __restrict__ VT, const bf16_t* __restrict__ G, bf16_t* __restrict__ MIX) {
;     ...
;                 { const float z = p0[r]; const float lg = (z > 30.f) ? z : lg2(1.0f + ex2(z)); const bool valid = !diag || (kv0 + crow(r, hi) < tq); L0[r] = valid ? -lg : 0.f; p0[r] = valid ? (z - lg) : -1e30f; }
;                 { const float z = p1[r]; const float lg = (z > 30.f) ? z : lg2(1.0f + ex2(z)); const bool valid = !diag || (kv0 + 32 + crow(r, hi) < tq); L1[r] = valid ? -lg : 0.f; p1[r] = valid ? (z - lg) : -1e30f; }
;             }
;             const bf16x8 Lh0 = pack8<0>(L0), Lh1 = pack8<1>(L0), Lh2 = pack8<0>(L1), Lh3 = pack8<1>(L1);
;             f32x16 C0 = splat16(carry), C1 = C0;
;             C0 = MFMA32(tp0, Lh0, C0); C0 = MFMA32(tp1, Lh1, C0); C0 = MFMA32(ones, Lh2, C0); C0 = MFMA32(ones, Lh3, C0);
;             C1 = MFMA32(tp0, Lh2, C1); C1 = MFMA32(tp1, Lh3, C1);
;             const float cn = C0[0] + L0[0];
;             carry = __shfl(cn, r32, 64);
; #pragma unroll
;             for (int r = 0; r < 16; ++r) { p0[r] = ex2(p0[r] + C0[r]); p1[r] = ex2(p1[r] + C1[r]); }
;             const bf16x8 pa0 = pack8<0>(p0), pa1 = pack8<1>(p0), pa2 = pack8<0>(p1), pa3 = pack8<1>(p1);
;     ...
;             SB_PV(0, pa0) SB_PV(1, pa1) SB_PV(2, pa2) SB_PV(3, pa3)
	s_or_b64 vcc, s[0:1], vcc
	v_sub_f32_e32 v29, v29, v59
	v_cndmask_b32_e64 v12, 0, -v59, vcc
	v_cndmask_b32_e32 v59, v237, v29, vcc
	v_exp_f32_e32 v29, v13
	v_cmp_lt_f32_e32 vcc, s22, v13
	v_add_f32_e32 v29, 1.0, v29
	v_log_f32_e32 v29, v29
	s_nop 0
	v_cndmask_b32_e32 v60, v29, v13, vcc
	v_or_b32_e32 v29, 51, v41
	v_cmp_lt_i32_e32 vcc, v29, v101
	s_or_b64 vcc, s[0:1], vcc
	v_sub_f32_e32 v13, v13, v60
	v_cndmask_b32_e64 v29, 0, -v60, vcc
	v_cndmask_b32_e32 v60, v237, v13, vcc
	v_exp_f32_e32 v13, v30
	v_cmp_lt_f32_e32 vcc, s22, v30
	v_cvt_pk_bf16_f32 v109, v28, v29
	v_add_f32_e32 v13, 1.0, v13
	v_log_f32_e32 v13, v13
	s_nop 0
	v_cndmask_b32_e32 v13, v13, v30, vcc
	v_cmp_lt_i32_e32 vcc, v61, v101
	s_or_b64 vcc, s[0:1], vcc
	s_nop 0
	v_cndmask_b32_e64 v66, 0, -v13, vcc
	v_sub_f32_e32 v13, v30, v13
	v_cndmask_b32_e32 v61, v237, v13, vcc
	v_exp_f32_e32 v13, v14
	v_cmp_lt_f32_e32 vcc, s22, v14
	v_or_b32_e32 v30, 56, v41
	v_add_f32_e32 v13, 1.0, v13
	v_log_f32_e32 v13, v13
	s_nop 0
	v_cndmask_b32_e32 v13, v13, v14, vcc
	v_cmp_lt_i32_e32 vcc, v30, v101
	s_or_b64 vcc, s[0:1], vcc
	v_or_b32_e32 v30, 57, v41
	v_cndmask_b32_e64 v67, 0, -v13, vcc
	v_sub_f32_e32 v13, v14, v13
	v_cndmask_b32_e32 v62, v237, v13, vcc
	v_exp_f32_e32 v13, v31
	v_cmp_lt_f32_e32 vcc, s22, v31
	v_or_b32_e32 v14, 25, v41
	v_add_f32_e32 v13, 1.0, v13
	v_log_f32_e32 v13, v13
	s_nop 0
	v_cndmask_b32_e32 v13, v13, v31, vcc
	v_cmp_lt_i32_e32 vcc, v14, v101
	s_or_b64 vcc, s[0:1], vcc
	s_nop 0
	v_cndmask_b32_e64 v14, 0, -v13, vcc
	v_sub_f32_e32 v13, v31, v13
	v_cndmask_b32_e32 v63, v237, v13, vcc
	v_exp_f32_e32 v13, v15
	v_cmp_lt_f32_e32 vcc, s22, v15
	v_cvt_pk_bf16_f32 v31, v11, v12
	v_add_f32_e32 v13, 1.0, v13
	v_log_f32_e32 v13, v13
	s_nop 0
	v_cndmask_b32_e32 v13, v13, v15, vcc
	v_cmp_lt_i32_e32 vcc, v30, v101
	s_or_b64 vcc, s[0:1], vcc
	v_or_b32_e32 v30, 58, v41
	v_cndmask_b32_e64 v110, 0, -v13, vcc
	v_sub_f32_e32 v13, v15, v13
	v_cndmask_b32_e32 v64, v237, v13, vcc
	v_exp_f32_e32 v13, v32
	v_cmp_lt_f32_e32 vcc, s22, v32
	v_or_b32_e32 v15, 26, v41
	v_cvt_pk_bf16_f32 v110, v67, v110
	v_add_f32_e32 v13, 1.0, v13
	v_log_f32_e32 v13, v13
	s_nop 0
	v_cndmask_b32_e32 v13, v13, v32, vcc
	v_cmp_lt_i32_e32 vcc, v15, v101
	s_or_b64 vcc, s[0:1], vcc
	s_nop 0
	v_cndmask_b32_e64 v15, 0, -v13, vcc
	v_sub_f32_e32 v13, v32, v13
	v_cndmask_b32_e32 v65, v237, v13, vcc
	v_exp_f32_e32 v13, v16
	v_cmp_lt_f32_e32 vcc, s22, v16
	v_cvt_pk_bf16_f32 v32, v66, v14
	v_add_f32_e32 v13, 1.0, v13
	v_log_f32_e32 v13, v13
	s_nop 0
	v_cndmask_b32_e32 v13, v13, v16, vcc
	v_cmp_lt_i32_e32 vcc, v30, v101
	s_or_b64 vcc, s[0:1], vcc
	v_or_b32_e32 v30, 59, v41
	v_cndmask_b32_e64 v111, 0, -v13, vcc
	v_sub_f32_e32 v13, v16, v13
	v_cndmask_b32_e32 v112, v237, v13, vcc
	v_exp_f32_e32 v13, v33
	v_cmp_lt_f32_e32 vcc, s22, v33
	v_or_b32_e32 v16, 27, v41
	v_add_f32_e32 v13, 1.0, v13
	v_log_f32_e32 v13, v13
	s_nop 0
	v_cndmask_b32_e32 v13, v13, v33, vcc
	v_cmp_lt_i32_e32 vcc, v16, v101
	s_or_b64 vcc, s[0:1], vcc
	s_nop 0
	v_cndmask_b32_e64 v16, 0, -v13, vcc
	v_sub_f32_e32 v13, v33, v13
	v_cndmask_b32_e32 v113, v237, v13, vcc
	v_exp_f32_e32 v13, v17
	v_cmp_lt_f32_e32 vcc, s22, v17
	v_cvt_pk_bf16_f32 v33, v15, v16
	v_add_f32_e32 v13, 1.0, v13
	v_log_f32_e32 v13, v13
	s_nop 0
	v_cndmask_b32_e32 v13, v13, v17, vcc
	v_cmp_lt_i32_e32 vcc, v30, v101
	s_or_b64 vcc, s[0:1], vcc
	v_cvt_pk_bf16_f32 v30, v9, v10
	v_cndmask_b32_e64 v41, 0, -v13, vcc
	v_sub_f32_e32 v13, v17, v13
	v_cndmask_b32_e32 v114, v237, v13, vcc
	v_mfma_f32_32x32x16_bf16 v[2:17], v[84:87], v[2:5], 0
	v_cvt_pk_bf16_f32 v111, v111, v41
	v_and_or_b32 v41, v238, 64, v100
	v_lshlrev_b32_e32 v41, 2, v41
	s_mov_b32 s0, s4
	v_writelane_b32 v254, s0, 48
	v_mfma_f32_32x32x16_bf16 v[2:17], v[88:91], v[30:33], v[2:17]
	s_nop 0
	v_writelane_b32 v254, s1, 49
	v_writelane_b32 v254, s2, 50
	v_writelane_b32 v254, s3, 51
	s_mov_b32 s0, 0xc3180000
	v_mfma_f32_32x32x16_bf16 v[2:17], v[22:25], v[18:21], v[2:17]
	v_mfma_f32_32x32x16_bf16 v[2:17], v[22:25], v[108:111], v[2:17]
	v_mfma_f32_32x32x16_bf16 v[18:33], v[84:87], v[18:21], 0
	s_nop 10
	v_add_f32_e32 v10, v10, v53
	v_add_f32_e32 v11, v11, v55
	v_add_f32_e32 v34, v34, v2
	v_add_f32_e32 v2, v2, v36
	v_add_f32_e32 v3, v3, v38
	v_add_f32_e32 v4, v4, v40
	v_add_f32_e32 v5, v5, v43
	v_mfma_f32_32x32x16_bf16 v[18:33], v[88:91], v[108:111], v[18:33]
	v_add_f32_e32 v6, v6, v45
	v_add_f32_e32 v7, v7, v47
	v_add_f32_e32 v8, v8, v49
	v_add_f32_e32 v9, v9, v51
	v_exp_f32_e32 v10, v10
	v_exp_f32_e32 v11, v11
	v_add_f32_e32 v12, v12, v57
	v_add_f32_e32 v13, v13, v59
	v_exp_f32_e32 v2, v2
	v_exp_f32_e32 v3, v3
	v_exp_f32_e32 v4, v4
	v_exp_f32_e32 v5, v5
	v_exp_f32_e32 v6, v6
	v_exp_f32_e32 v7, v7
	v_exp_f32_e32 v8, v8
	v_exp_f32_e32 v9, v9
	v_exp_f32_e32 v12, v12
	v_exp_f32_e32 v13, v13
	v_add_f32_e32 v21, v44, v21
	v_cvt_pk_bf16_f32 v44, v10, v11
	v_add3_u32 v10, 0, v104, v103
	v_add_f32_e32 v18, v37, v18
	v_add_f32_e32 v19, v39, v19
	v_add_f32_e32 v20, v42, v20
	v_add_f32_e32 v22, v46, v22
	v_add_f32_e32 v23, v48, v23
	v_add_f32_e32 v24, v50, v24
	v_add_f32_e32 v25, v52, v25
	v_add_f32_e32 v26, v54, v26
	v_add_f32_e32 v27, v56, v27
	v_add_f32_e32 v28, v58, v28
	v_add_f32_e32 v29, v60, v29
	v_add_f32_e32 v14, v14, v61
	v_add_f32_e32 v30, v62, v30
	v_add_f32_e32 v15, v15, v63
	v_add_f32_e32 v31, v64, v31
	v_add_f32_e32 v16, v16, v65
	v_add_f32_e32 v32, v112, v32
	v_add_f32_e32 v17, v17, v113
	v_add_f32_e32 v33, v114, v33
	v_cvt_pk_bf16_f32 v2, v2, v3
	v_cvt_pk_bf16_f32 v3, v4, v5
	v_cvt_pk_bf16_f32 v4, v6, v7
	v_cvt_pk_bf16_f32 v5, v8, v9
	v_cvt_pk_bf16_f32 v45, v12, v13
	ds_read_b128 v[6:9], v10 offset:8192
	ds_read_b128 v[10:13], v10 offset:12288
	v_exp_f32_e32 v18, v18
	v_exp_f32_e32 v19, v19
	v_exp_f32_e32 v20, v20
	v_exp_f32_e32 v21, v21
	v_exp_f32_e32 v22, v22
	v_exp_f32_e32 v23, v23
	v_exp_f32_e32 v24, v24
	v_exp_f32_e32 v25, v25
	v_exp_f32_e32 v26, v26
	v_exp_f32_e32 v27, v27
	v_exp_f32_e32 v28, v28
	v_exp_f32_e32 v29, v29
	v_exp_f32_e32 v14, v14
	v_exp_f32_e32 v30, v30
	v_exp_f32_e32 v15, v15
	v_exp_f32_e32 v31, v31
	v_exp_f32_e32 v16, v16
	v_exp_f32_e32 v32, v32
	v_exp_f32_e32 v17, v17
	v_exp_f32_e32 v33, v33
	ds_bpermute_b32 v34, v41, v34
	v_cvt_pk_bf16_f32 v46, v14, v15
	v_cvt_pk_bf16_f32 v47, v16, v17
	v_cvt_pk_bf16_f32 v40, v18, v19
	v_cvt_pk_bf16_f32 v41, v20, v21
	v_cvt_pk_bf16_f32 v42, v22, v23
	v_cvt_pk_bf16_f32 v43, v24, v25
	v_cvt_pk_bf16_f32 v36, v26, v27
	v_cvt_pk_bf16_f32 v37, v28, v29
	v_cvt_pk_bf16_f32 v38, v30, v31
	v_cvt_pk_bf16_f32 v39, v32, v33
	s_waitcnt lgkmcnt(2)
; template <int S> DI bf16x8 pack8(const f32x16& x) { u32x4 p; p[0] = cvtpk(x[8 * S], x[8 * S + 1]); p[1] = cvtpk(x[8 * S + 2], x[8 * S + 3]); p[2] = cvtpk(x[8 * S + 4], x[8 * S + 5]); p[3] = cvtpk(x[8 * S + 6], x[8 * S + 7]); return __builtin_bit_cast(bf16x8, p); }
; #define SB_PV(ks, pa) { const bf16x8 v0 = ldsv(Vt + off128(r32, 2 * (ks) + hi)), v1 = ldsv(Vt + off128(32 + r32, 2 * (ks) + hi)); o0 = MFMA32(v0, pa, o0); o1 = MFMA32(v1, pa, o1); }
; DI void sb_unit(LAS char* lds, int b, int h, int qb, const bf16_t* __restrict__ Q, const bf16_t* __restrict__ K, const bf16_t* __restrict__ VT, const bf16_t* __restrict__ G, bf16_t* __restrict__ MIX) {
;     ...
;             const bf16x8 pa0 = pack8<0>(p0), pa1 = pack8<1>(p0), pa2 = pack8<0>(p1), pa3 = pack8<1>(p1);
;     ...
;             SB_PV(0, pa0) SB_PV(1, pa1) SB_PV(2, pa2) SB_PV(3, pa3)
;     ...
;             done = __all(carry < -152.f) ? 1 : 0;
;         }
	v_mfma_f32_32x32x16_bf16 v[18:33], v[6:9], v[2:5], 0
	v_add3_u32 v52, 0, v105, v103
	ds_read_b128 v[48:51], v52 offset:8192
	ds_read_b128 v[52:55], v52 offset:12288
	s_waitcnt lgkmcnt(2)
	v_cmp_gt_f32_e32 vcc, s0, v34
	s_cmp_eq_u64 vcc, exec
	s_cselect_b64 s[0:1], -1, 0
	v_mfma_f32_32x32x16_bf16 v[2:17], v[10:13], v[2:5], 0
	s_waitcnt lgkmcnt(1)
	v_mfma_f32_32x32x16_bf16 v[18:33], v[48:51], v[44:47], v[18:33]
	v_add3_u32 v48, 0, v106, v103
	s_waitcnt lgkmcnt(0)
	v_mfma_f32_32x32x16_bf16 v[2:17], v[52:55], v[44:47], v[2:17]
	ds_read_b128 v[44:47], v48 offset:8192
	ds_read_b128 v[48:51], v48 offset:12288
	s_waitcnt lgkmcnt(1)
	v_mfma_f32_32x32x16_bf16 v[18:33], v[44:47], v[40:43], v[18:33]
	v_add3_u32 v44, 0, v107, v103
	s_waitcnt lgkmcnt(0)
	v_mfma_f32_32x32x16_bf16 v[2:17], v[48:51], v[40:43], v[2:17]
	ds_read_b128 v[40:43], v44 offset:8192
	ds_read_b128 v[44:47], v44 offset:12288
	s_waitcnt lgkmcnt(1)
	v_mfma_f32_32x32x16_bf16 v[18:33], v[40:43], v[36:39], v[18:33]
	s_waitcnt lgkmcnt(0)
	v_mfma_f32_32x32x16_bf16 v[2:17], v[44:47], v[36:39], v[2:17]
	v_cndmask_b32_e64 v36, 0, 1, s[0:1]
	s_branch .LBB0_414

; #define LAS __attribute__((address_space(3)))
; DI float ex2(float x) { return __builtin_amdgcn_exp2f(x); }
; #define WAIT_BAR0() asm volatile("s_waitcnt vmcnt(0) lgkmcnt(0)\n\ts_barrier" ::: "memory")
; DI void df_unit(LAS char* lds, int b, int h, int qb, const bf16_t* __restrict__ Q, const bf16_t* __restrict__ K, const bf16_t* __restrict__ VT, const bf16_t* __restrict__ G, bf16_t* __restrict__ MIX,
;                 float lam, float Mb  , const float* __restrict__ subg) {
;     ...
;     const int tid = tid_, lane = tid & 63, r32 = lane & 31, hi = lane >> 5; const int wid = __builtin_amdgcn_readfirstlane(tid >> 6);
;     const int mp = wid >> 2, wq = wid & 3;
;     const int q0 = qb * 128, qw0 = q0 + 32 * wq, tq = qw0 + r32;
;     LAS float* Xch = (LAS float*)lds;
;     const unsigned lds0 = (unsigned)(uintptr_t)lds;
;     DfCtx c; c.qw0 = qw0; c.tq = 0; c.hi = 0;
; #pragma unroll
;     for (int d0 = 0; d0 < 4; ++d0) c.qf[d0] = *(const bf16x8*)(Q + (size_t)(b * SEQ + tq) * 512 + h * 128 + mp * 64 + d0 * 16 + hi * 8);
;     { const int kx = hi ^ (r32 & 15), vx = hi ^ ((r32 >> 1) & 7);
; #pragma unroll
;       for (int i = 0; i < 4; ++i) { c.kad[i] = r32 * 256 + (((8 * mp + 2 * i) ^ kx) << 4); c.vad[i] = r32 * 128 + (((2 * i) ^ vx) << 4); } }
;     const int krow = 4 * wid + (lane >> 4), kch = (lane & 15) ^ (krow & 15);
;     const int vrow = 8 * wid + (lane >> 3), vch = (lane & 7) ^ ((vrow >> 1) & 7);
;     const bf16_t* ksrc = K + (size_t)(b * SEQ + krow) * 512 + h * 128 + kch * 8;
;     const bf16_t* vsrc = VT + (size_t)(b * 4 + h) * (SEQ * 128) + vrow * 64 + vch * 8;
;     ...
;     f32x16 O[4];
; #pragma unroll
;     for (int i = 0; i < 4; ++i) O[i] = splat16(0.f);
;     float l = 0.f;
;     const float slope2 = ex2(-2.0f * (float)(h + 1)) * LOG2E;
;     c.sl = slope2; c.c0 = -slope2 * (float)(tq - 4 * hi) - Mb;
;     const int nt = (q0 + 128) / 64;
;     int T0 = 0; { float mb2 = Mb; asm volatile("" : "+s"(mb2)); const int W = (int)ceilf((150.0f + 2.0f * mb2) / slope2) + 1; const int x = q0 - 63 - W; if (x >= 0) T0 = x / 64 + 1; }
;     WAIT_BAR0();
;     DF_DMA(T0, 0, 0); if (T0 + 1 < nt) DF_DMA(T0 + 1, 16384, 16384);
.LBB0_373:
	v_mov_b32_e32 v42, v236
	s_lshl_b32 s45, s15, 7
	v_readfirstlane_b32 s0, v42
	s_ashr_i32 s4, s0, 6
	s_ashr_i32 s6, s0, 8
	v_writelane_b32 v255, s0, 18
	s_and_b32 s0, s4, 3
	s_lshl_b32 s61, s0, 5
	v_and_b32_e32 v41, 31, v42
	v_writelane_b32 v255, s0, 19
	s_or_b32 s0, s61, s45
	v_or_b32_e32 v44, s0, v41
	s_lshl_b32 s5, s14, 13
	v_add_u32_e32 v2, s5, v44
	v_writelane_b32 v255, s0, 20
	v_ashrrev_i32_e32 v3, 31, v2
	v_readlane_b32 s0, v253, 8
	v_lshlrev_b64 v[2:3], 10, v[2:3]
	v_readlane_b32 s1, v253, 9
	s_lshl_b32 s98, s16, 8
	v_bfe_u32 v43, v42, 5, 1
	v_lshl_add_u64 v[2:3], s[0:1], 0, v[2:3]
	s_lshl_b32 s0, s6, 6
	v_lshl_add_u64 v[2:3], v[2:3], 0, s[98:99]
	s_ashr_i32 s1, s0, 31
	v_lshl_add_u64 v[2:3], s[0:1], 1, v[2:3]
	v_lshlrev_b32_e32 v0, 4, v43
	v_lshl_add_u64 v[2:3], v[2:3], 0, v[0:1]
	global_load_dwordx4 v[130:133], v[2:3], off
	global_load_dwordx4 v[134:137], v[2:3], off offset:32
	global_load_dwordx4 v[138:141], v[2:3], off offset:64
	global_load_dwordx4 v[142:145], v[2:3], off offset:96
	v_bfe_u32 v39, v42, 3, 3
	v_writelane_b32 v255, s6, 21
	s_lshl_b32 s0, s4, 2
	v_bfe_u32 v250, v42, 4, 2
	v_lshl_or_b32 v4, s4, 3, v39
	v_or_b32_e32 v0, s0, v250
	v_writelane_b32 v255, s0, 22
	v_bitop3_b32 v38, s0, v42, v250 bitop3:0x36
	v_lshrrev_b32_e32 v2, 1, v4
	s_lshl_b32 s0, s14, 2
	v_xor_b32_e32 v40, v2, v42
	v_add_u32_e32 v2, s5, v0
	s_add_i32 s0, s0, s16
	s_mov_b32 s1, s99
	v_ashrrev_i32_e32 v3, 31, v2
	s_lshl_b64 s[6:7], s[0:1], 21
	v_readlane_b32 s0, v253, 10
	v_lshlrev_b64 v[2:3], 10, v[2:3]
	v_readlane_b32 s1, v253, 11
	v_writelane_b32 v255, s5, 23
	v_lshlrev_b32_e32 v4, 6, v4
	v_lshl_add_u64 v[2:3], s[0:1], 0, v[2:3]
	v_readlane_b32 s0, v253, 16
	v_readlane_b32 s1, v253, 17
	s_add_u32 s0, s0, s6
	v_ashrrev_i32_e32 v5, 31, v4
	v_writelane_b32 v255, s6, 24
	s_addc_u32 s1, s1, s7
	v_lshlrev_b32_e32 v0, 4, v38
	v_writelane_b32 v255, s7, 25
	v_lshl_add_u64 v[4:5], v[4:5], 1, s[0:1]
	s_mov_b32 s0, s16
	v_lshl_add_u64 v[2:3], v[2:3], 0, s[98:99]
	v_and_b32_e32 v0, 0xf0, v0
	v_writelane_b32 v255, s0, 26
	v_lshl_add_u64 v[2:3], v[2:3], 0, v[0:1]
	v_lshlrev_b32_e32 v0, 4, v40
	v_writelane_b32 v255, s1, 27
	s_not_b32 s0, s16
	v_and_b32_e32 v0, 0x70, v0
	s_lshl_b32 s0, s0, 1
	v_lshl_add_u64 v[4:5], v[4:5], 0, v[0:1]
	v_cvt_f32_i32_e32 v0, s0
	s_add_i32 s0, s45, 0x80
	s_ashr_i32 s23, s0, 6
	v_readlane_b32 s0, v254, 63
	v_exp_f32_e32 v7, v0
	s_waitcnt lgkmcnt(0)
	s_nop 0
	s_nop 0
	v_mov_b32_e32 v6, s0
	v_readlane_b32 s0, v254, 52
	v_readlane_b32 s1, v254, 53
	s_mov_b32 s0, s8
	s_mov_b32 s5, s1
	v_pk_mul_f32 v[178:179], v[6:7], s[0:1]
	v_writelane_b32 v254, s4, 52
	v_add_f32_e32 v0, 0x43160000, v178
	v_div_scale_f32 v6, s[0:1], v179, v179, v0
	v_rcp_f32_e32 v7, v6
	v_writelane_b32 v254, s5, 53
	v_fma_f32 v8, -v6, v7, 1.0
	v_fmac_f32_e32 v7, v8, v7
	v_div_scale_f32 v8, vcc, v0, v179, v0
	v_mul_f32_e32 v9, v8, v7
	v_fma_f32 v10, -v6, v9, v8
	v_fmac_f32_e32 v9, v10, v7
	v_fma_f32 v6, -v6, v9, v8
	v_div_fmas_f32 v6, v6, v7, v9
	v_div_fixup_f32 v0, v6, v179, v0
	v_ceil_f32_e32 v0, v0
	v_cvt_i32_f32_e32 v0, v0
	s_nop 0
	v_readfirstlane_b32 s0, v0
	s_not_b32 s0, s0
	s_add_i32 s0, s45, s0
	s_sub_i32 s0, s0, 63
	s_lshr_b32 s1, s0, 6
	s_add_i32 s1, s1, 1
	s_cmp_gt_i32 s0, -1
	s_cselect_b32 s98, s1, 0
	s_lshl_b32 s6, s4, 10
	s_lshl_b64 s[24:25], s[98:99], 16
	s_add_i32 s5, s6, 0
	v_lshl_add_u64 v[6:7], v[2:3], 0, s[24:25]
	s_mov_b32 s0, m0
	s_mov_b32 m0, s5
	s_nop 0
	global_load_lds_dwordx4 v[6:7], off
	s_mov_b32 m0, s0
	s_mov_b64 s[0:1], 0x8000
	s_lshl_b64 s[26:27], s[98:99], 14
	v_lshl_add_u64 v[6:7], v[6:7], 0, s[0:1]
	s_add_i32 s7, s5, 0x2000
	s_mov_b32 s0, m0
	s_mov_b32 m0, s7
	s_nop 0
	global_load_lds_dwordx4 v[6:7], off
	s_mov_b32 m0, s0
	s_add_i32 s14, s5, 0x10000
	v_lshl_add_u64 v[8:9], v[4:5], 0, s[26:27]
	s_mov_b32 s0, m0
	s_mov_b32 m0, s14
	s_nop 0
	global_load_lds_dwordx4 v[8:9], off
	s_mov_b32 m0, s0
	s_mov_b64 s[0:1], 0x2000
	v_lshl_add_u64 v[6:7], v[8:9], 0, s[0:1]
	s_add_i32 s44, s5, 0x12000
	s_mov_b32 s0, m0
	s_mov_b32 m0, s44
	s_nop 0
	global_load_lds_dwordx4 v[6:7], off
	s_mov_b32 m0, s0
	s_add_i32 s60, s98, 1
	s_mov_b64 s[0:1], -1
	s_cmp_ge_i32 s60, s23
	s_cbranch_scc0 .LBB0_382
	s_waitcnt vmcnt(0) lgkmcnt(0)
	s_barrier
	s_cbranch_execz .LBB0_383
